# G6 and G4 K-loops: activation (A) operand LDS-DMA loads marked nt (streamed once per XCD), weights stay default
# speedup vs baseline: 1.0318x; 1.0036x over previous
.LBB0_227:
	s_xor_b32 s14, s13, 0x22000
	v_add_u32_e32 v133, s14, v180
	v_lshl_add_u64 v[130:131], v[134:135], 0, s[4:5]
	v_readfirstlane_b32 s15, v133
	s_nop 0
	s_mov_b32 m0, s15
	s_nop 0
	global_load_lds_dwordx4 v[130:131], off nt
	v_add_u32_e32 v133, s14, v179
	v_lshl_add_u64 v[130:131], v[136:137], 0, s[4:5]
	v_readfirstlane_b32 s15, v133
	s_nop 0
	s_mov_b32 m0, s15
	s_nop 0
	global_load_lds_dwordx4 v[130:131], off nt
	v_add_u32_e32 v133, s14, v178
	v_lshl_add_u64 v[130:131], v[138:139], 0, s[4:5]
	v_readfirstlane_b32 s15, v133
	s_nop 0
	s_mov_b32 m0, s15
	s_nop 0
	global_load_lds_dwordx4 v[130:131], off nt
	v_add_u32_e32 v249, 0x8000, v248
	v_add_u32_e32 v133, v249, v180
	v_lshl_add_u64 v[130:131], v[142:143], 0, s[4:5]
	v_readfirstlane_b32 s15, v133
	s_nop 0
	s_mov_b32 m0, s15
	s_nop 0
	global_load_lds_dwordx4 v[130:131], off
	v_add_u32_e32 v133, v249, v179
	v_lshl_add_u64 v[130:131], v[144:145], 0, s[4:5]
	v_readfirstlane_b32 s15, v133
	s_nop 0
	s_mov_b32 m0, s15
	s_nop 0
	global_load_lds_dwordx4 v[130:131], off
	v_add_u32_e32 v133, v249, v178
	v_lshl_add_u64 v[130:131], v[146:147], 0, s[4:5]
	v_readfirstlane_b32 s15, v133
	s_nop 0
	s_mov_b32 m0, s15
	s_nop 0
	global_load_lds_dwordx4 v[130:131], off
	v_add_u32_e32 v133, v249, v177
	v_lshl_add_u64 v[130:131], v[148:149], 0, s[4:5]
	v_readfirstlane_b32 s15, v133
	s_nop 0
	s_mov_b32 m0, s15
	s_nop 0
	global_load_lds_dwordx4 v[130:131], off
.LBB0_228:
	s_or_b64 exec, exec, s[6:7]
	s_add_i32 s6, s13, 0
	v_add_u32_e32 v131, s6, v182
	v_add_u32_e32 v130, v246, v183
	v_add_u32_e32 v133, v131, v184
	v_add_u32_e32 v230, v130, v184
	ds_read_b128 v[190:193], v133
	ds_read_b128 v[194:197], v133 offset:4096
	ds_read_b128 v[198:201], v133 offset:8192
	ds_read_b128 v[206:209], v230 offset:32768
	ds_read_b128 v[210:213], v230 offset:36864
	v_add_u32_e32 v133, v131, v181
	v_add_u32_e32 v230, v130, v181
	s_setprio 1
	s_waitcnt lgkmcnt(0)
	v_mfma_f32_32x32x16_bf16 v[112:127], v[190:193], v[206:209], v[112:127]
	ds_read_b128 v[214:217], v133
	v_mfma_f32_32x32x16_bf16 v[96:111], v[190:193], v[210:213], v[96:111]
	ds_read_b128 v[218:221], v133 offset:4096
	v_mfma_f32_32x32x16_bf16 v[80:95], v[194:197], v[206:209], v[80:95]
	ds_read_b128 v[234:237], v133 offset:8192
	v_mfma_f32_32x32x16_bf16 v[64:79], v[194:197], v[210:213], v[64:79]
	ds_read_b128 v[238:241], v230 offset:32768
	v_mfma_f32_32x32x16_bf16 v[48:63], v[198:201], v[206:209], v[48:63]
	ds_read_b128 v[242:245], v230 offset:36864
	v_mfma_f32_32x32x16_bf16 v[32:47], v[198:201], v[210:213], v[32:47]
	s_setprio 0
	v_add_u32_e32 v133, v131, v172
	v_add_u32_e32 v230, v130, v172
	s_setprio 1
	s_waitcnt lgkmcnt(0)
	v_mfma_f32_32x32x16_bf16 v[112:127], v[214:217], v[238:241], v[112:127]
	ds_read_b128 v[190:193], v133
	v_mfma_f32_32x32x16_bf16 v[96:111], v[214:217], v[242:245], v[96:111]
	ds_read_b128 v[194:197], v133 offset:4096
	v_mfma_f32_32x32x16_bf16 v[80:95], v[218:221], v[238:241], v[80:95]
	ds_read_b128 v[198:201], v133 offset:8192
	v_mfma_f32_32x32x16_bf16 v[64:79], v[218:221], v[242:245], v[64:79]
	ds_read_b128 v[206:209], v230 offset:32768
	v_mfma_f32_32x32x16_bf16 v[48:63], v[234:237], v[238:241], v[48:63]
	ds_read_b128 v[210:213], v230 offset:36864
	v_mfma_f32_32x32x16_bf16 v[32:47], v[234:237], v[242:245], v[32:47]
	s_setprio 0
	s_and_saveexec_b64 s[6:7], s[0:1]
	s_cbranch_execz .LBB0_230
	s_xor_b32 s14, s13, 0x22000
	v_add_u32_e32 v133, s14, v180
	v_lshl_add_u64 v[228:229], v[150:151], 0, s[4:5]
	v_readfirstlane_b32 s15, v133
	s_nop 0
	s_mov_b32 m0, s15
	s_nop 0
	global_load_lds_dwordx4 v[228:229], off nt
	v_add_u32_e32 v133, s14, v179
	v_lshl_add_u64 v[228:229], v[152:153], 0, s[4:5]
	v_readfirstlane_b32 s15, v133
	s_nop 0
	s_mov_b32 m0, s15
	s_nop 0
	global_load_lds_dwordx4 v[228:229], off nt
	v_add_u32_e32 v133, s14, v178
	v_lshl_add_u64 v[228:229], v[154:155], 0, s[4:5]
	v_readfirstlane_b32 s15, v133
	s_nop 0
	s_mov_b32 m0, s15
	s_nop 0
	global_load_lds_dwordx4 v[228:229], off nt
	v_add_u32_e32 v249, 0x8000, v248
	v_add_u32_e32 v133, v249, v180
	v_lshl_add_u64 v[228:229], v[158:159], 0, s[4:5]
	v_readfirstlane_b32 s15, v133
	s_nop 0
	s_mov_b32 m0, s15
	s_nop 0
	global_load_lds_dwordx4 v[228:229], off
	v_add_u32_e32 v133, v249, v179
	v_lshl_add_u64 v[228:229], v[160:161], 0, s[4:5]
	v_readfirstlane_b32 s15, v133
	s_nop 0
	s_mov_b32 m0, s15
	s_nop 0
	global_load_lds_dwordx4 v[228:229], off
	v_add_u32_e32 v133, v249, v178
	v_lshl_add_u64 v[228:229], v[162:163], 0, s[4:5]
	v_readfirstlane_b32 s15, v133
	s_nop 0
	s_mov_b32 m0, s15
	s_nop 0
	global_load_lds_dwordx4 v[228:229], off
	v_add_u32_e32 v133, v249, v177
	v_lshl_add_u64 v[228:229], v[164:165], 0, s[4:5]
	v_readfirstlane_b32 s15, v133
	s_nop 0
	s_mov_b32 m0, s15
	s_nop 0
	global_load_lds_dwordx4 v[228:229], off

.LBB0_270:
	s_xor_b32 s14, s13, 0x10000
	s_add_i32 s14, s14, 0
	v_add_u32_e32 v133, s14, v177
	v_add_u32_e32 v186, s14, v176
	v_readfirstlane_b32 s15, v133
	v_lshl_add_u64 v[130:131], v[134:135], 0, s[4:5]
	s_mov_b32 m0, s15
	v_readfirstlane_b32 s15, v186
	v_add_u32_e32 v187, s14, v175
	global_load_lds_dwordx4 v[130:131], off nt
	v_lshl_add_u64 v[130:131], v[136:137], 0, s[4:5]
	s_mov_b32 m0, s15
	v_readfirstlane_b32 s15, v187
	v_add_u32_e32 v188, s14, v174
	global_load_lds_dwordx4 v[130:131], off nt
	v_lshl_add_u64 v[130:131], v[138:139], 0, s[4:5]
	s_mov_b32 m0, s15
	v_readfirstlane_b32 s14, v188
	v_add_u32_e32 v133, 0x8000, v133
	global_load_lds_dwordx4 v[130:131], off nt
	v_readfirstlane_b32 s14, v133
	v_add_u32_e32 v133, 0x8000, v186
	v_lshl_add_u64 v[130:131], v[142:143], 0, s[4:5]
	s_mov_b32 m0, s14
	v_readfirstlane_b32 s14, v133
	v_add_u32_e32 v133, 0x8000, v187
	global_load_lds_dwordx4 v[130:131], off
	v_lshl_add_u64 v[130:131], v[144:145], 0, s[4:5]
	s_mov_b32 m0, s14
	v_readfirstlane_b32 s14, v133
	v_add_u32_e32 v133, 0x8000, v188
	global_load_lds_dwordx4 v[130:131], off
	v_lshl_add_u64 v[130:131], v[146:147], 0, s[4:5]
	s_mov_b32 m0, s14
	v_readfirstlane_b32 s14, v133
	global_load_lds_dwordx4 v[130:131], off
	v_lshl_add_u64 v[130:131], v[148:149], 0, s[4:5]
	s_mov_b32 m0, s14
	s_nop 0
	global_load_lds_dwordx4 v[130:131], off
.LBB0_271:
	s_or_b64 exec, exec, s[6:7]
	s_add_i32 s6, s13, 0
	v_add_u32_e32 v131, s6, v178
	v_add_u32_e32 v133, v131, v181
	v_add_u32_e32 v130, s6, v180
	ds_read_b128 v[186:189], v133
	ds_read_b128 v[190:193], v133 offset:4096
	ds_read_b128 v[194:197], v133 offset:8192
	v_add_u32_e32 v133, v130, v181
	ds_read_b128 v[202:205], v133 offset:32768
	ds_read_b128 v[206:209], v133 offset:36864
	s_setprio 1
	s_waitcnt lgkmcnt(0)
	v_mfma_f32_32x32x16_bf16 v[112:127], v[186:189], v[202:205], v[112:127]
	v_mfma_f32_32x32x16_bf16 v[96:111], v[186:189], v[206:209], v[96:111]
	v_mfma_f32_32x32x16_bf16 v[80:95], v[190:193], v[202:205], v[80:95]
	v_mfma_f32_32x32x16_bf16 v[64:79], v[190:193], v[206:209], v[64:79]
	v_mfma_f32_32x32x16_bf16 v[48:63], v[194:197], v[202:205], v[48:63]
	v_mfma_f32_32x32x16_bf16 v[32:47], v[194:197], v[206:209], v[32:47]
	s_setprio 0
	v_add_u32_e32 v133, v131, v179
	ds_read_b128 v[186:189], v133
	ds_read_b128 v[190:193], v133 offset:4096
	ds_read_b128 v[194:197], v133 offset:8192
	v_add_u32_e32 v133, v130, v179
	ds_read_b128 v[202:205], v133 offset:32768
	ds_read_b128 v[206:209], v133 offset:36864
	s_setprio 1
	s_waitcnt lgkmcnt(0)
	v_mfma_f32_32x32x16_bf16 v[112:127], v[186:189], v[202:205], v[112:127]
	v_mfma_f32_32x32x16_bf16 v[96:111], v[186:189], v[206:209], v[96:111]
	v_mfma_f32_32x32x16_bf16 v[80:95], v[190:193], v[202:205], v[80:95]
	v_mfma_f32_32x32x16_bf16 v[64:79], v[190:193], v[206:209], v[64:79]
	v_mfma_f32_32x32x16_bf16 v[48:63], v[194:197], v[202:205], v[48:63]
	v_mfma_f32_32x32x16_bf16 v[32:47], v[194:197], v[206:209], v[32:47]
	s_setprio 0
	s_and_saveexec_b64 s[6:7], s[0:1]
	s_cbranch_execz .LBB0_273
	s_xor_b32 s13, s13, 0x10000
	s_add_i32 s13, s13, 0
	v_add_u32_e32 v133, s13, v177
	v_add_u32_e32 v188, s13, v176
	v_readfirstlane_b32 s14, v133
	v_lshl_add_u64 v[186:187], v[150:151], 0, s[4:5]
	s_mov_b32 m0, s14
	v_readfirstlane_b32 s14, v188
	v_add_u32_e32 v189, s13, v175
	global_load_lds_dwordx4 v[186:187], off nt
	v_lshl_add_u64 v[186:187], v[152:153], 0, s[4:5]
	s_mov_b32 m0, s14
	v_readfirstlane_b32 s14, v189
	v_add_u32_e32 v190, s13, v174
	global_load_lds_dwordx4 v[186:187], off nt
	v_lshl_add_u64 v[186:187], v[154:155], 0, s[4:5]
	s_mov_b32 m0, s14
	v_readfirstlane_b32 s13, v190
	v_add_u32_e32 v133, 0x8000, v133
	global_load_lds_dwordx4 v[186:187], off nt
	v_readfirstlane_b32 s13, v133
	v_add_u32_e32 v133, 0x8000, v188
	v_lshl_add_u64 v[186:187], v[158:159], 0, s[4:5]
	s_mov_b32 m0, s13
	v_readfirstlane_b32 s13, v133
	v_add_u32_e32 v133, 0x8000, v189
	global_load_lds_dwordx4 v[186:187], off
	v_lshl_add_u64 v[186:187], v[160:161], 0, s[4:5]
	s_mov_b32 m0, s13
	v_readfirstlane_b32 s13, v133
	v_add_u32_e32 v133, 0x8000, v190
	global_load_lds_dwordx4 v[186:187], off
	v_lshl_add_u64 v[186:187], v[162:163], 0, s[4:5]
	s_mov_b32 m0, s13
	v_readfirstlane_b32 s13, v133
	global_load_lds_dwordx4 v[186:187], off
	v_lshl_add_u64 v[186:187], v[164:165], 0, s[4:5]
	s_mov_b32 m0, s13
	s_nop 0
	global_load_lds_dwordx4 v[186:187], off
